# attention loop: pipelined LDS reads + static s_setprio 1 for waves 4-7, in-loop setprio flips removed
# speedup vs baseline: 1.0025x; 1.0025x over previous
.LBB0_710:
	v_mul_f32_e32 v0, v102, v0
	v_mul_f32_e32 v0, v0, v227
	v_mul_f32_e32 v1, v102, v1
	v_mul_f32_e32 v2, v102, v2
	v_mul_f32_e32 v1, v1, v226
	v_mul_f32_e32 v2, v2, v225
	v_mul_f32_e32 v3, v102, v3
	v_mul_f32_e32 v0, 0x3dd53b94, v0
	v_mul_f32_e32 v3, v3, v231
	v_mul_f32_e32 v1, 0x3dd53b94, v1
	v_cvt_pk_bf16_f32 v130, v0, v1
	v_mul_f32_e32 v0, 0x3dd53b94, v2
	v_mul_f32_e32 v1, 0x3dd53b94, v3
	v_cvt_pk_bf16_f32 v131, v0, v1
	v_mul_f32_e32 v0, 0x3dd53b94, v100
	v_mul_f32_e32 v1, 0x3dd53b94, v101
	v_cvt_pk_bf16_f32 v100, v0, v1
	v_mul_f32_e32 v0, 0x3dd53b94, v98
	v_mul_f32_e32 v1, 0x3dd53b94, v99
	v_cvt_pk_bf16_f32 v101, v0, v1
	v_mul_f32_e32 v0, 0x3dd53b94, v96
	v_mul_f32_e32 v60, v60, v102
	v_mul_f32_e32 v61, v61, v102
	v_mul_f32_e32 v62, v62, v102
	v_mul_f32_e32 v63, v63, v102
	v_mul_f32_e32 v56, v56, v102
	v_mul_f32_e32 v57, v57, v102
	v_mul_f32_e32 v58, v58, v102
	v_mul_f32_e32 v59, v59, v102
	v_mul_f32_e32 v52, v52, v102
	v_mul_f32_e32 v53, v102, v53
	v_mul_f32_e32 v54, v102, v54
	v_mul_f32_e32 v55, v102, v55
	v_mul_f32_e32 v48, v102, v48
	v_mul_f32_e32 v49, v102, v49
	v_mul_f32_e32 v50, v102, v50
	v_mul_f32_e32 v51, v102, v51
	v_mul_f32_e32 v44, v102, v44
	v_mul_f32_e32 v45, v102, v45
	v_mul_f32_e32 v46, v102, v46
	v_mul_f32_e32 v47, v102, v47
	v_mul_f32_e32 v40, v102, v40
	v_mul_f32_e32 v41, v102, v41
	v_mul_f32_e32 v42, v102, v42
	v_mul_f32_e32 v43, v102, v43
	v_mul_f32_e32 v36, v102, v36
	v_mul_f32_e32 v37, v102, v37
	v_mul_f32_e32 v38, v102, v38
	v_mul_f32_e32 v39, v102, v39
	v_mul_f32_e32 v32, v102, v32
	v_mul_f32_e32 v33, v102, v33
	v_mul_f32_e32 v34, v102, v34
	v_mul_f32_e32 v35, v102, v35
	v_mul_f32_e32 v28, v102, v28
	v_mul_f32_e32 v29, v102, v29
	v_mul_f32_e32 v30, v102, v30
	v_mul_f32_e32 v31, v102, v31
	v_mul_f32_e32 v24, v102, v24
	v_mul_f32_e32 v25, v102, v25
	v_mul_f32_e32 v26, v102, v26
	v_mul_f32_e32 v27, v102, v27
	v_mul_f32_e32 v20, v102, v20
	v_mul_f32_e32 v21, v102, v21
	v_mul_f32_e32 v22, v102, v22
	v_mul_f32_e32 v23, v102, v23
	v_mul_f32_e32 v16, v102, v16
	v_mul_f32_e32 v17, v102, v17
	v_mul_f32_e32 v18, v102, v18
	v_mul_f32_e32 v19, v102, v19
	v_mul_f32_e32 v12, v102, v12
	v_mul_f32_e32 v13, v102, v13
	v_mul_f32_e32 v14, v102, v14
	v_mul_f32_e32 v15, v102, v15
	v_mul_f32_e32 v8, v102, v8
	v_mul_f32_e32 v9, v102, v9
	v_mul_f32_e32 v10, v102, v10
	v_mul_f32_e32 v11, v102, v11
	v_mul_f32_e32 v4, v102, v4
	v_mul_f32_e32 v5, v102, v5
	v_mul_f32_e32 v6, v102, v6
	v_mul_f32_e32 v7, v102, v7
	v_mul_f32_e32 v1, 0x3dd53b94, v97
	v_cvt_pk_bf16_f32 v102, v0, v1
	v_mul_f32_e32 v0, 0x3dd53b94, v158
	v_mul_f32_e32 v11, v11, v103
	v_mul_f32_e32 v1, 0x3dd53b94, v159
	v_cvt_pk_bf16_f32 v103, v0, v1
	v_mul_f32_e32 v0, 0x3dd53b94, v154
	v_mul_f32_e32 v1, 0x3dd53b94, v155
	v_cvt_pk_bf16_f32 v96, v0, v1
	v_mul_f32_e32 v0, 0x3dd53b94, v74
	v_mul_f32_e32 v1, 0x3dd53b94, v75
	v_cvt_pk_bf16_f32 v97, v0, v1
	v_mul_f32_e32 v0, 0x3dd53b94, v72
	v_mul_f32_e32 v1, 0x3dd53b94, v73
	v_cvt_pk_bf16_f32 v98, v0, v1
	v_mul_f32_e32 v0, 0x3dd53b94, v156
	v_mul_f32_e32 v1, 0x3dd53b94, v157
	v_cvt_pk_bf16_f32 v99, v0, v1
	v_mul_hi_i32 v0, v84, s44
	v_lshrrev_b32_e32 v1, 31, v0
	v_ashrrev_i32_e32 v0, 2, v0
	v_add_u32_e32 v2, v0, v1
	v_mad_u64_u32 v[0:1], s[20:21], v2, s46, v[84:85]
	v_lshrrev_b32_e32 v1, 1, v2
	v_bitop3_b32 v1, v1, 7, v84 bitop3:0x48
	v_and_or_b32 v0, v0, s45, v1
	v_mul_lo_u32 v1, v2, s23
	v_lshl_add_u32 v164, v0, 4, v1
	v_add_u32_e32 v0, 0x200, v84
	v_mul_hi_i32 v1, v0, s44
	v_lshrrev_b32_e32 v2, 31, v1
	v_ashrrev_i32_e32 v1, 2, v1
	v_add_u32_e32 v1, v1, v2
	v_mad_u64_u32 v[2:3], s[20:21], v1, s46, v[0:1]
	v_lshrrev_b32_e32 v3, 1, v1
	s_lshl_b64 s[0:1], s[12:13], 1
	v_bitop3_b32 v3, v3, 7, v84 bitop3:0x48
	s_add_u32 s6, s41, s0
	v_and_or_b32 v2, v2, s45, v3
	v_mul_lo_u32 v1, v1, s23
	s_addc_u32 s7, s40, s1
	v_lshl_add_u32 v154, v2, 4, v1
	v_add_u32_e32 v2, 0x400, v84
	s_add_u32 s12, s6, 0x1a678000
	v_mul_hi_i32 v1, v2, s44
	s_addc_u32 s13, s7, 0
	v_lshrrev_b32_e32 v3, 31, v1
	v_ashrrev_i32_e32 v1, 2, v1
	s_add_u32 s15, s39, 0x12878000
	v_add_u32_e32 v1, v1, v3
	s_addc_u32 s16, s38, 0
	v_mad_u64_u32 v[2:3], s[20:21], v1, s46, v[2:3]
	s_and_b64 s[0:1], exec, s[10:11]
	v_lshrrev_b32_e32 v3, 1, v1
	s_movk_i32 s0, 0x1100
	v_bitop3_b32 v3, v3, 7, v84 bitop3:0x48
	s_cselect_b32 s0, 0x100, s0
	v_and_or_b32 v2, v2, s45, v3
	v_mul_lo_u32 v1, v1, s23
	s_lshr_b32 s17, s0, 6
	v_lshl_add_u32 v156, v2, 4, v1
	s_lshl_b32 s0, s0, 1
	v_ashrrev_i32_e32 v2, 3, v84
	v_ashrrev_i32_e32 v0, 3, v0
	v_lshlrev_b32_e32 v1, 4, v84
	s_movk_i32 s1, 0x70
	v_mul_lo_u32 v2, s0, v2
	v_mul_lo_u32 v0, s0, v0
	s_lshl_b32 s0, s25, 12
	v_bitop3_b32 v1, v1, s1, v84 bitop3:0x48
	s_addk_i32 s0, 0x2000
	s_lshl_b32 s1, s25, 8
	s_and_b64 s[10:11], exec, s[10:11]
	s_cselect_b32 s10, s1, s0
	s_ashr_i32 s11, s10, 31
	s_lshl_b64 s[10:11], s[10:11], 3
	s_add_u32 s10, s10, s4
	s_addc_u32 s11, s11, s5
	s_mulk_i32 s11, 0x180
	s_mul_hi_u32 s20, s10, 0x180
	v_mul_f32_e32 v14, v14, v161
	v_lshlrev_b32_e32 v161, 10, v160
	s_add_i32 s20, s20, s11
	s_mulk_i32 s10, 0x180
	v_mul_f32_e32 v13, v13, v162
	s_add_u32 s10, s15, s10
	v_add_u32_e32 v162, 0, v161
	v_or_b32_e32 v2, v2, v1
	v_or_b32_e32 v0, v0, v1
	s_addc_u32 s11, s16, s20
	v_readfirstlane_b32 s20, v162
	v_add_u32_e32 v1, 0x2000, v162
	s_mov_b32 m0, s20
	v_readfirstlane_b32 s20, v1
	v_add_u32_e32 v1, 0x4000, v162
	s_barrier
	global_load_lds_dwordx4 v164, s[10:11]
	s_mov_b32 m0, s20
	v_readfirstlane_b32 s20, v1
	global_load_lds_dwordx4 v154, s[10:11]
	s_mov_b32 m0, s20
	v_add_u32_e32 v1, 0x6000, v162
	global_load_lds_dwordx4 v156, s[10:11]
	v_readfirstlane_b32 s10, v1
	v_add_u32_e32 v1, 0x8000, v162
	s_mov_b32 m0, s10
	v_readfirstlane_b32 s10, v1
	global_load_lds_dwordx4 v2, s[12:13]
	s_mov_b32 m0, s10
	v_mul_f32_e32 v1, 0x3dd53b94, v140
	global_load_lds_dwordx4 v0, s[12:13]
	v_mul_f32_e32 v3, 0x3dd53b94, v109
	v_cvt_pk_bf16_f32 v140, v1, v3
	v_mul_f32_e32 v1, 0x3dd53b94, v148
	v_mul_f32_e32 v3, 0x3dd53b94, v111
	v_cvt_pk_bf16_f32 v141, v1, v3
	v_mul_f32_e32 v1, 0x3dd53b94, v150
	v_mul_f32_e32 v3, 0x3dd53b94, v95
	v_cvt_pk_bf16_f32 v142, v1, v3
	v_mul_f32_e32 v1, 0x3dd53b94, v152
	v_mul_f32_e32 v3, 0x3dd53b94, v143
	v_cvt_pk_bf16_f32 v143, v1, v3
	v_mul_f32_e32 v1, 0x3dd53b94, v86
	v_mul_f32_e32 v3, 0x3dd53b94, v87
	v_cvt_pk_bf16_f32 v108, v1, v3
	v_mul_f32_e32 v1, 0x3dd53b94, v92
	v_mul_f32_e32 v3, 0x3dd53b94, v93
	v_mul_f32_e32 v5, v5, v229
	v_cvt_pk_bf16_f32 v109, v1, v3
	v_mul_f32_e32 v1, 0x3dd53b94, v88
	v_mul_f32_e32 v3, 0x3dd53b94, v89
	v_mul_f32_e32 v4, v4, v224
	v_mul_f32_e32 v7, v7, v228
	v_mul_f32_e32 v5, 0x3dd53b94, v5
	v_cvt_pk_bf16_f32 v110, v1, v3
	v_mul_f32_e32 v1, 0x3dd53b94, v90
	v_mul_f32_e32 v3, 0x3dd53b94, v91
	v_mul_f32_e32 v6, v6, v230
	v_mul_f32_e32 v4, 0x3dd53b94, v4
	v_cvt_pk_bf16_f32 v128, v4, v5
	v_mul_f32_e32 v5, 0x3dd53b94, v7
	v_cvt_pk_bf16_f32 v111, v1, v3
	v_lshrrev_b32_e32 v1, 1, v84
	v_bfe_u32 v3, v84, 1, 3
	v_mul_f32_e32 v4, 0x3dd53b94, v6
	v_cvt_pk_bf16_f32 v129, v4, v5
	v_bitop3_b32 v1, v147, v1, 7 bitop3:0x78
	v_bitop3_b32 v5, v147, v3, 2 bitop3:0x36
	v_bitop3_b32 v6, v147, v3, 4 bitop3:0x36
	v_bitop3_b32 v3, v147, v3, 6 bitop3:0x36
	v_mul_f32_e32 v60, v60, v222
	v_mul_f32_e32 v61, v61, v220
	v_mul_f32_e32 v56, v56, v214
	v_mul_f32_e32 v57, v57, v212
	v_mul_f32_e32 v52, v52, v223
	v_mul_f32_e32 v53, v53, v221
	v_mul_f32_e32 v48, v48, v215
	v_mul_f32_e32 v49, v49, v213
	v_mul_f32_e32 v44, v44, v207
	v_mul_f32_e32 v45, v45, v206
	v_mul_f32_e32 v40, v40, v203
	v_mul_f32_e32 v41, v41, v202
	v_mul_f32_e32 v36, v36, v199
	v_mul_f32_e32 v37, v37, v198
	v_mul_f32_e32 v32, v32, v185
	v_mul_f32_e32 v33, v33, v184
	v_mul_f32_e32 v28, v28, v181
	v_mul_f32_e32 v29, v29, v180
	v_mul_f32_e32 v24, v24, v177
	v_mul_f32_e32 v25, v25, v176
	v_mul_f32_e32 v20, v20, v173
	v_mul_f32_e32 v21, v21, v172
	v_mul_f32_e32 v16, v16, v169
	v_mul_f32_e32 v17, v17, v168
	v_mul_f32_e32 v12, v12, v163
	v_mul_f32_e32 v8, v8, v138
	v_mul_f32_e32 v9, v9, v137
	v_mul_u32_u24_e32 v4, 0x180, v85
	v_lshlrev_b32_e32 v1, 4, v1
	v_lshlrev_b32_e32 v5, 4, v5
	v_lshlrev_b32_e32 v6, 4, v6
	v_lshlrev_b32_e32 v3, 4, v3
	v_mul_f32_e32 v62, v62, v218
	v_mul_f32_e32 v63, v63, v216
	v_mul_f32_e32 v58, v58, v210
	v_mul_f32_e32 v59, v59, v208
	v_mul_f32_e32 v54, v54, v219
	v_mul_f32_e32 v55, v55, v217
	v_mul_f32_e32 v50, v50, v211
	v_mul_f32_e32 v51, v51, v209
	v_mul_f32_e32 v46, v46, v205
	v_mul_f32_e32 v47, v47, v204
	v_mul_f32_e32 v42, v42, v201
	v_mul_f32_e32 v43, v43, v200
	v_mul_f32_e32 v38, v38, v187
	v_mul_f32_e32 v39, v39, v186
	v_mul_f32_e32 v34, v34, v183
	v_mul_f32_e32 v35, v35, v182
	v_mul_f32_e32 v30, v30, v179
	v_mul_f32_e32 v31, v31, v178
	v_mul_f32_e32 v26, v26, v175
	v_mul_f32_e32 v27, v27, v174
	v_mul_f32_e32 v22, v22, v171
	v_mul_f32_e32 v23, v23, v170
	v_mul_f32_e32 v18, v18, v167
	v_mul_f32_e32 v19, v19, v166
	v_mul_f32_e32 v15, v15, v139
	v_mul_f32_e32 v10, v10, v136
	v_mul_f32_e32 v60, 0x3dd53b94, v60
	v_mul_f32_e32 v61, 0x3dd53b94, v61
	v_mul_f32_e32 v56, 0x3dd53b94, v56
	v_mul_f32_e32 v57, 0x3dd53b94, v57
	v_mul_f32_e32 v52, 0x3dd53b94, v52
	v_mul_f32_e32 v53, 0x3dd53b94, v53
	v_mul_f32_e32 v48, 0x3dd53b94, v48
	v_mul_f32_e32 v49, 0x3dd53b94, v49
	v_mul_f32_e32 v44, 0x3dd53b94, v44
	v_mul_f32_e32 v45, 0x3dd53b94, v45
	v_mul_f32_e32 v40, 0x3dd53b94, v40
	v_mul_f32_e32 v41, 0x3dd53b94, v41
	v_mul_f32_e32 v36, 0x3dd53b94, v36
	v_mul_f32_e32 v37, 0x3dd53b94, v37
	v_mul_f32_e32 v32, 0x3dd53b94, v32
	v_mul_f32_e32 v33, 0x3dd53b94, v33
	v_mul_f32_e32 v28, 0x3dd53b94, v28
	v_mul_f32_e32 v29, 0x3dd53b94, v29
	v_mul_f32_e32 v24, 0x3dd53b94, v24
	v_mul_f32_e32 v25, 0x3dd53b94, v25
	v_mul_f32_e32 v20, 0x3dd53b94, v20
	v_mul_f32_e32 v21, 0x3dd53b94, v21
	v_mul_f32_e32 v16, 0x3dd53b94, v16
	v_mul_f32_e32 v17, 0x3dd53b94, v17
	v_mul_f32_e32 v12, 0x3dd53b94, v12
	v_mul_f32_e32 v13, 0x3dd53b94, v13
	v_mul_f32_e32 v8, 0x3dd53b94, v8
	v_mul_f32_e32 v9, 0x3dd53b94, v9
	v_or_b32_e32 v168, v1, v4
	v_or_b32_e32 v167, v5, v4
	v_or_b32_e32 v166, v6, v4
	v_or_b32_e32 v163, v3, v4
	v_lshlrev_b32_e32 v4, 7, v85
	s_add_u32 s6, s6, 0x1a678080
	v_cvt_pk_bf16_f32 v116, v60, v61
	v_mul_f32_e32 v60, 0x3dd53b94, v62
	v_mul_f32_e32 v61, 0x3dd53b94, v63
	v_cvt_pk_bf16_f32 v118, v56, v57
	v_mul_f32_e32 v56, 0x3dd53b94, v58
	v_mul_f32_e32 v57, 0x3dd53b94, v59
	v_cvt_pk_bf16_f32 v124, v52, v53
	v_mul_f32_e32 v52, 0x3dd53b94, v54
	v_mul_f32_e32 v53, 0x3dd53b94, v55
	v_cvt_pk_bf16_f32 v126, v48, v49
	v_mul_f32_e32 v48, 0x3dd53b94, v50
	v_mul_f32_e32 v49, 0x3dd53b94, v51
	v_cvt_pk_bf16_f32 v132, v44, v45
	v_mul_f32_e32 v44, 0x3dd53b94, v46
	v_mul_f32_e32 v45, 0x3dd53b94, v47
	v_cvt_pk_bf16_f32 v134, v40, v41
	v_mul_f32_e32 v40, 0x3dd53b94, v42
	v_mul_f32_e32 v41, 0x3dd53b94, v43
	v_cvt_pk_bf16_f32 v136, v36, v37
	v_mul_f32_e32 v36, 0x3dd53b94, v38
	v_mul_f32_e32 v37, 0x3dd53b94, v39
	v_cvt_pk_bf16_f32 v138, v32, v33
	v_mul_f32_e32 v32, 0x3dd53b94, v34
	v_mul_f32_e32 v33, 0x3dd53b94, v35
	v_cvt_pk_bf16_f32 v104, v28, v29
	v_mul_f32_e32 v28, 0x3dd53b94, v30
	v_mul_f32_e32 v29, 0x3dd53b94, v31
	v_cvt_pk_bf16_f32 v106, v24, v25
	v_mul_f32_e32 v24, 0x3dd53b94, v26
	v_mul_f32_e32 v25, 0x3dd53b94, v27
	v_cvt_pk_bf16_f32 v112, v20, v21
	v_mul_f32_e32 v20, 0x3dd53b94, v22
	v_mul_f32_e32 v21, 0x3dd53b94, v23
	v_cvt_pk_bf16_f32 v114, v16, v17
	v_mul_f32_e32 v16, 0x3dd53b94, v18
	v_mul_f32_e32 v17, 0x3dd53b94, v19
	v_cvt_pk_bf16_f32 v120, v12, v13
	v_mul_f32_e32 v12, 0x3dd53b94, v14
	v_mul_f32_e32 v13, 0x3dd53b94, v15
	v_cvt_pk_bf16_f32 v122, v8, v9
	v_mul_f32_e32 v8, 0x3dd53b94, v10
	v_mul_f32_e32 v9, 0x3dd53b94, v11
	v_or_b32_e32 v159, v1, v4
	v_or_b32_e32 v152, v3, v4
	v_mov_b32_e32 v3, v165
	v_mov_b32_e32 v1, v165
	s_waitcnt vmcnt(0)
	s_addc_u32 s7, s7, 0
	v_mov_b32_e32 v14, v165
	v_mov_b32_e32 v15, v165
	v_cvt_pk_bf16_f32 v117, v60, v61
	v_cvt_pk_bf16_f32 v119, v56, v57
	v_cvt_pk_bf16_f32 v125, v52, v53
	v_cvt_pk_bf16_f32 v127, v48, v49
	v_cvt_pk_bf16_f32 v133, v44, v45
	v_cvt_pk_bf16_f32 v135, v40, v41
	v_cvt_pk_bf16_f32 v137, v36, v37
	v_cvt_pk_bf16_f32 v139, v32, v33
	v_cvt_pk_bf16_f32 v105, v28, v29
	v_cvt_pk_bf16_f32 v107, v24, v25
	v_cvt_pk_bf16_f32 v113, v20, v21
	v_cvt_pk_bf16_f32 v115, v16, v17
	v_cvt_pk_bf16_f32 v121, v12, v13
	v_cvt_pk_bf16_f32 v123, v8, v9
	v_or_b32_e32 v158, v5, v4
	v_or_b32_e32 v153, v6, v4
	v_lshl_add_u64 v[148:149], s[6:7], 0, v[0:1]
	v_lshl_add_u64 v[150:151], s[6:7], 0, v[2:3]
	v_mov_b32_e32 v0, v165
	v_mov_b32_e32 v2, v165
	v_mov_b32_e32 v4, v165
	v_mov_b32_e32 v5, v165
	v_mov_b32_e32 v6, v165
	v_mov_b32_e32 v7, v165
	v_mov_b32_e32 v8, v165
	v_mov_b32_e32 v9, v165
	v_mov_b32_e32 v10, v165
	v_mov_b32_e32 v11, v165
	v_mov_b32_e32 v12, v165
	v_mov_b32_e32 v13, v165
	v_mov_b64_e32 v[30:31], v[14:15]
	v_mov_b64_e32 v[46:47], v[14:15]
	v_mov_b64_e32 v[62:63], v[14:15]
	s_mov_b32 s14, 1
	v_mov_b32_e32 v155, v165
	v_mov_b32_e32 v157, v165
	s_mov_b32 s12, 0
	v_mov_b32_e32 v147, 0
	v_mov_b32_e32 v160, 0xff800000
	s_mov_b32 s13, 0x9040
	v_mov_b64_e32 v[28:29], v[12:13]
	v_mov_b64_e32 v[26:27], v[10:11]
	v_mov_b64_e32 v[24:25], v[8:9]
	v_mov_b64_e32 v[22:23], v[6:7]
	v_mov_b64_e32 v[20:21], v[4:5]
	v_mov_b64_e32 v[18:19], v[2:3]
	v_mov_b64_e32 v[16:17], v[0:1]
	v_mov_b64_e32 v[44:45], v[12:13]
	v_mov_b64_e32 v[42:43], v[10:11]
	v_mov_b64_e32 v[40:41], v[8:9]
	v_mov_b64_e32 v[38:39], v[6:7]
	v_mov_b64_e32 v[36:37], v[4:5]
	v_mov_b64_e32 v[34:35], v[2:3]
	v_mov_b64_e32 v[32:33], v[0:1]
	v_mov_b64_e32 v[60:61], v[12:13]
	v_mov_b64_e32 v[58:59], v[10:11]
	v_mov_b64_e32 v[56:57], v[8:9]
	v_mov_b64_e32 v[54:55], v[6:7]
	v_mov_b64_e32 v[52:53], v[4:5]
	v_mov_b64_e32 v[50:51], v[2:3]
	v_mov_b64_e32 v[48:49], v[0:1]
	s_waitcnt vmcnt(0) lgkmcnt(0)
	s_barrier
	v_readfirstlane_b32 s101, v188
	s_nop 3
	s_lshr_b32 s101, s101, 8
	s_cmp_eq_u32 s101, 0
	s_cbranch_scc1 .Lattn_prio_done
	s_setprio 1

.LBB0_711:
	v_sub_f32_e32 v80, v80, v160
	v_exp_f32_e32 v80, v80
	v_sub_f32_e32 v81, v81, v160
	v_sub_f32_e32 v82, v82, v160
	v_exp_f32_e32 v81, v81
	v_sub_f32_e32 v64, v64, v160
	v_exp_f32_e32 v82, v82
	v_sub_f32_e32 v83, v83, v160
	v_exp_f32_e32 v170, v64
	v_sub_f32_e32 v64, v65, v160
	v_exp_f32_e32 v83, v83
	v_sub_f32_e32 v84, v84, v160
	v_exp_f32_e32 v171, v64
	v_sub_f32_e32 v64, v66, v160
	v_add_f32_e32 v169, 0, v80
	v_exp_f32_e32 v84, v84
	v_sub_f32_e32 v85, v85, v160
	v_exp_f32_e32 v172, v64
	v_sub_f32_e32 v64, v67, v160
	v_add_f32_e32 v169, v81, v169
	v_exp_f32_e32 v85, v85
	v_sub_f32_e32 v86, v86, v160
	v_exp_f32_e32 v173, v64
	v_sub_f32_e32 v64, v68, v160
	v_add_f32_e32 v169, v82, v169
	v_exp_f32_e32 v86, v86
	v_sub_f32_e32 v87, v87, v160
	v_exp_f32_e32 v174, v64
	v_sub_f32_e32 v64, v69, v160
	v_add_f32_e32 v169, v83, v169
	v_exp_f32_e32 v87, v87
	v_sub_f32_e32 v88, v88, v160
	v_exp_f32_e32 v175, v64
	v_sub_f32_e32 v64, v70, v160
	v_add_f32_e32 v169, v84, v169
	v_exp_f32_e32 v88, v88
	v_sub_f32_e32 v89, v89, v160
	v_exp_f32_e32 v176, v64
	v_sub_f32_e32 v64, v71, v160
	v_add_f32_e32 v169, v85, v169
	v_exp_f32_e32 v89, v89
	v_sub_f32_e32 v90, v90, v160
	v_exp_f32_e32 v177, v64
	v_sub_f32_e32 v64, v72, v160
	v_add_f32_e32 v169, v86, v169
	v_exp_f32_e32 v90, v90
	v_sub_f32_e32 v91, v91, v160
	v_exp_f32_e32 v72, v64
	v_sub_f32_e32 v64, v73, v160
	v_add_f32_e32 v169, v87, v169
	v_exp_f32_e32 v91, v91
	v_sub_f32_e32 v92, v92, v160
	v_exp_f32_e32 v73, v64
	v_sub_f32_e32 v64, v74, v160
	v_add_f32_e32 v169, v88, v169
	v_exp_f32_e32 v92, v92
	v_sub_f32_e32 v93, v93, v160
	v_exp_f32_e32 v74, v64
	v_sub_f32_e32 v64, v75, v160
	v_add_f32_e32 v169, v89, v169
	v_exp_f32_e32 v93, v93
	v_sub_f32_e32 v94, v94, v160
	v_exp_f32_e32 v75, v64
	v_sub_f32_e32 v64, v76, v160
	v_add_f32_e32 v169, v90, v169
	v_exp_f32_e32 v94, v94
	v_sub_f32_e32 v95, v95, v160
	v_exp_f32_e32 v76, v64
	v_sub_f32_e32 v64, v77, v160
	v_add_f32_e32 v169, v91, v169
	v_exp_f32_e32 v95, v95
	v_exp_f32_e32 v77, v64
	v_sub_f32_e32 v64, v78, v160
	v_add_f32_e32 v169, v92, v169
	v_exp_f32_e32 v78, v64
	v_sub_f32_e32 v64, v79, v160
	v_exp_f32_e32 v79, v64
	v_add_f32_e32 v64, v93, v169
	v_add_f32_e32 v64, v94, v64
	v_add_f32_e32 v169, v95, v64
	v_cvt_pk_bf16_f32 v64, v80, v81
	v_cvt_pk_bf16_f32 v65, v82, v83
	v_cvt_pk_bf16_f32 v66, v84, v85
	v_cvt_pk_bf16_f32 v67, v86, v87
	s_waitcnt lgkmcnt(0)
	s_nop 0
	v_mfma_f32_32x32x16_bf16 v[48:63], v[178:181], v[64:67], v[48:63]
	v_mfma_f32_32x32x16_bf16 v[32:47], v[182:185], v[64:67], v[32:47]
	v_mfma_f32_32x32x16_bf16 v[16:31], v[198:201], v[64:67], v[16:31]
	v_mfma_f32_32x32x16_bf16 v[0:15], v[202:205], v[64:67], v[0:15]
	ds_read_b128 v[178:181], v247 offset:24576
	ds_read_b128 v[182:185], v247 offset:28672
	ds_read_b128 v[198:201], v247 offset:32768
	ds_read_b128 v[202:205], v247 offset:36864
	v_cvt_pk_bf16_f32 v64, v88, v89
	v_cvt_pk_bf16_f32 v65, v90, v91
	v_cvt_pk_bf16_f32 v66, v92, v93
	v_cvt_pk_bf16_f32 v67, v94, v95
	s_nop 1
	v_mfma_f32_32x32x16_bf16 v[48:63], v[206:209], v[64:67], v[48:63]
	v_mfma_f32_32x32x16_bf16 v[32:47], v[210:213], v[64:67], v[32:47]
	v_mfma_f32_32x32x16_bf16 v[16:31], v[214:217], v[64:67], v[16:31]
	v_mfma_f32_32x32x16_bf16 v[0:15], v[218:221], v[64:67], v[0:15]
	v_cvt_pk_bf16_f32 v64, v170, v171
	v_cvt_pk_bf16_f32 v65, v172, v173
	v_cvt_pk_bf16_f32 v66, v174, v175
	v_cvt_pk_bf16_f32 v67, v176, v177
	s_nop 1
	v_mfma_f32_32x32x16_bf16 v[48:63], v[222:225], v[64:67], v[48:63]
	v_mfma_f32_32x32x16_bf16 v[32:47], v[226:229], v[64:67], v[32:47]
	v_mfma_f32_32x32x16_bf16 v[16:31], v[230:233], v[64:67], v[16:31]
	v_mfma_f32_32x32x16_bf16 v[0:15], v[240:243], v[64:67], v[0:15]
	v_cvt_pk_bf16_f32 v64, v72, v73
	v_cvt_pk_bf16_f32 v65, v74, v75
	v_cvt_pk_bf16_f32 v66, v76, v77
	v_cvt_pk_bf16_f32 v67, v78, v79
	s_waitcnt lgkmcnt(0)
	s_nop 0
	v_mfma_f32_32x32x16_bf16 v[48:63], v[178:181], v[64:67], v[48:63]
	v_mfma_f32_32x32x16_bf16 v[32:47], v[182:185], v[64:67], v[32:47]
	v_mfma_f32_32x32x16_bf16 v[16:31], v[198:201], v[64:67], v[16:31]
	v_mfma_f32_32x32x16_bf16 v[0:15], v[202:205], v[64:67], v[0:15]
	v_add_f32_e32 v64, v170, v169
	v_add_f32_e32 v64, v171, v64
	v_add_f32_e32 v64, v172, v64
	v_add_f32_e32 v64, v173, v64
	v_add_f32_e32 v64, v174, v64
	v_add_f32_e32 v64, v175, v64
	v_add_f32_e32 v64, v176, v64
	v_add_f32_e32 v64, v177, v64
	v_add_f32_e32 v64, v72, v64
	v_add_f32_e32 v64, v73, v64
	v_add_f32_e32 v64, v74, v64
	v_add_f32_e32 v64, v75, v64
	v_add_f32_e32 v64, v76, v64
	v_add_f32_e32 v64, v77, v64
	v_add_f32_e32 v64, v78, v64
	v_add_f32_e32 v64, v79, v64
	v_add_f32_e32 v147, v147, v64
	s_waitcnt vmcnt(0)
	s_add_i32 s14, s14, 1
	s_add_i32 s13, s13, 64
	v_lshl_add_u64 v[148:149], v[148:149], 0, s[18:19]
	s_cmp_eq_u32 s17, s14
	v_lshl_add_u64 v[150:151], v[150:151], 0, s[18:19]
	s_waitcnt vmcnt(0)
	s_barrier
	s_cbranch_scc1 .LBB0_722
.LBB0_712:
	s_bitcmp1_b32 s14, 0
	s_cselect_b32 s100, 0, 0xa000
	v_add_u32_e32 v169, s100, v168
	v_add_u32_e32 v174, s100, v167
	v_add_u32_e32 v175, s100, v166
	v_add_u32_e32 v176, s100, v163
	ds_read_b128 v[178:181], v169
	ds_read_b128 v[182:185], v169 offset:12288
	ds_read_b128 v[198:201], v174
	ds_read_b128 v[202:205], v174 offset:12288
	ds_read_b128 v[206:209], v175
	ds_read_b128 v[210:213], v175 offset:12288
	ds_read_b128 v[214:217], v176
	ds_read_b128 v[218:221], v176 offset:12288
	ds_read_b128 v[222:225], v169 offset:128
	ds_read_b128 v[226:229], v169 offset:12416
	ds_read_b128 v[230:233], v174 offset:128
	ds_read_b128 v[240:243], v174 offset:12416
	v_add_u32_e32 v244, s100, v159
	v_add_u32_e32 v245, s100, v158
	v_add_u32_e32 v246, s100, v153
	v_add_u32_e32 v247, s100, v152
	s_add_i32 s12, s12, 1
	s_lshl_b32 s11, s12, 6
	s_and_b64 vcc, exec, s[36:37]
	s_mov_b64 s[6:7], -1
	s_cbranch_vccnz .LBB0_718
	s_add_i32 s6, s13, 0xffff7000
	s_cmpk_gt_u32 s6, 0xfff
	s_mov_b64 s[6:7], -1
	s_cbranch_scc0 .LBB0_715
	s_add_i32 s10, s1, s13
	s_mov_b64 s[6:7], 0

.LBB0_720:
	s_ashr_i32 s11, s10, 31
	s_lshl_b64 s[6:7], s[10:11], 3
	s_add_u32 s6, s6, s4
	s_addc_u32 s7, s7, s5
	s_mulk_i32 s7, 0x180
	s_mul_hi_u32 s10, s6, 0x180
	s_add_i32 s10, s10, s7
	s_mulk_i32 s6, 0x180
	s_add_u32 s6, s15, s6
	s_addc_u32 s7, s16, s10
	s_bitcmp1_b32 s14, 0
	s_cselect_b32 s10, 0xa000, 0
	v_add_u32_e32 v66, s10, v162
	v_add_u32_e32 v67, 0x2000, v66
	v_readfirstlane_b32 s11, v66
	v_lshl_add_u64 v[64:65], s[6:7], 0, v[164:165]
	s_mov_b32 m0, s11
	v_readfirstlane_b32 s11, v67
	global_load_lds_dwordx4 v[64:65], off
	v_lshl_add_u64 v[64:65], s[6:7], 0, v[154:155]
	s_mov_b32 m0, s11
	v_add_u32_e32 v66, 0x4000, v66
	global_load_lds_dwordx4 v[64:65], off
	v_lshl_add_u64 v[64:65], s[6:7], 0, v[156:157]
	v_readfirstlane_b32 s6, v66
	s_mov_b32 m0, s6
	s_cselect_b32 s7, 0, 0xa000
	s_add_i32 s6, s10, 0
	global_load_lds_dwordx4 v[64:65], off
	v_add_u32_e32 v64, s6, v161
	v_add_u32_e32 v65, 0x6000, v64
	v_add_u32_e32 v64, 0x8000, v64
	v_readfirstlane_b32 s10, v65
	s_mov_b32 m0, s10
	v_readfirstlane_b32 s10, v64
	global_load_lds_dwordx4 v[150:151], off
	s_mov_b32 m0, s10
	s_add_i32 s7, s7, 0
	global_load_lds_dwordx4 v[148:149], off
	s_waitcnt lgkmcnt(11)
	v_mfma_f32_32x32x16_bf16 v[80:95], v[178:181], v[116:119], 0
	ds_read_b128 v[178:181], v175 offset:128
	s_waitcnt lgkmcnt(11)
	v_mfma_f32_32x32x16_bf16 v[64:79], v[182:185], v[116:119], 0
	ds_read_b128 v[182:185], v175 offset:12416
	s_waitcnt lgkmcnt(11)
	v_mfma_f32_32x32x16_bf16 v[80:95], v[198:201], v[124:127], v[80:95]
	ds_read_b128 v[198:201], v176 offset:128
	s_waitcnt lgkmcnt(11)
	v_mfma_f32_32x32x16_bf16 v[64:79], v[202:205], v[124:127], v[64:79]
	ds_read_b128 v[202:205], v176 offset:12416
	s_waitcnt lgkmcnt(11)
	v_mfma_f32_32x32x16_bf16 v[80:95], v[206:209], v[132:135], v[80:95]
	ds_read_b128 v[206:209], v169 offset:256
	s_waitcnt lgkmcnt(11)
	v_mfma_f32_32x32x16_bf16 v[64:79], v[210:213], v[132:135], v[64:79]
	ds_read_b128 v[210:213], v169 offset:12544
	s_waitcnt lgkmcnt(11)
	v_mfma_f32_32x32x16_bf16 v[80:95], v[214:217], v[136:139], v[80:95]
	ds_read_b128 v[214:217], v174 offset:256
	s_waitcnt lgkmcnt(11)
	v_mfma_f32_32x32x16_bf16 v[64:79], v[218:221], v[136:139], v[64:79]
	ds_read_b128 v[218:221], v174 offset:12544
	s_waitcnt lgkmcnt(11)
	v_mfma_f32_32x32x16_bf16 v[80:95], v[222:225], v[104:107], v[80:95]
	ds_read_b128 v[222:225], v175 offset:256
	s_waitcnt lgkmcnt(11)
	v_mfma_f32_32x32x16_bf16 v[64:79], v[226:229], v[104:107], v[64:79]
	ds_read_b128 v[226:229], v175 offset:12544
	s_waitcnt lgkmcnt(11)
	v_mfma_f32_32x32x16_bf16 v[80:95], v[230:233], v[112:115], v[80:95]
	ds_read_b128 v[230:233], v176 offset:256
	s_waitcnt lgkmcnt(11)
	v_mfma_f32_32x32x16_bf16 v[64:79], v[240:243], v[112:115], v[64:79]
	ds_read_b128 v[240:243], v176 offset:12544
	s_waitcnt lgkmcnt(11)
	v_mfma_f32_32x32x16_bf16 v[80:95], v[178:181], v[120:123], v[80:95]
	s_waitcnt lgkmcnt(10)
	v_mfma_f32_32x32x16_bf16 v[64:79], v[182:185], v[120:123], v[64:79]
	s_waitcnt lgkmcnt(9)
	v_mfma_f32_32x32x16_bf16 v[80:95], v[198:201], v[128:131], v[80:95]
	s_waitcnt lgkmcnt(8)
	v_mfma_f32_32x32x16_bf16 v[64:79], v[202:205], v[128:131], v[64:79]
	s_waitcnt lgkmcnt(7)
	v_mfma_f32_32x32x16_bf16 v[80:95], v[206:209], v[100:103], v[80:95]
	s_waitcnt lgkmcnt(6)
	v_mfma_f32_32x32x16_bf16 v[64:79], v[210:213], v[100:103], v[64:79]
	s_waitcnt lgkmcnt(5)
	v_mfma_f32_32x32x16_bf16 v[80:95], v[214:217], v[96:99], v[80:95]
	s_waitcnt lgkmcnt(4)
	v_mfma_f32_32x32x16_bf16 v[64:79], v[218:221], v[96:99], v[64:79]
	s_waitcnt lgkmcnt(3)
	v_mfma_f32_32x32x16_bf16 v[80:95], v[222:225], v[140:143], v[80:95]
	s_waitcnt lgkmcnt(2)
	v_mfma_f32_32x32x16_bf16 v[64:79], v[226:229], v[140:143], v[64:79]
	s_waitcnt lgkmcnt(1)
	v_mfma_f32_32x32x16_bf16 v[80:95], v[230:233], v[108:111], v[80:95]
	s_waitcnt lgkmcnt(0)
	v_mfma_f32_32x32x16_bf16 v[64:79], v[240:243], v[108:111], v[64:79]
	ds_read_b128 v[178:181], v244 offset:24576
	ds_read_b128 v[182:185], v244 offset:28672
	ds_read_b128 v[198:201], v244 offset:32768
	ds_read_b128 v[202:205], v244 offset:36864
	ds_read_b128 v[206:209], v245 offset:24576
	ds_read_b128 v[210:213], v245 offset:28672
	ds_read_b128 v[214:217], v245 offset:32768
	ds_read_b128 v[218:221], v245 offset:36864
	ds_read_b128 v[222:225], v246 offset:24576
	ds_read_b128 v[226:229], v246 offset:28672
	ds_read_b128 v[230:233], v246 offset:32768
	ds_read_b128 v[240:243], v246 offset:36864
	v_max_f32_e32 v169, v81, v81
	v_max_f32_e32 v170, v80, v80
	v_max_f32_e32 v169, v170, v169
	v_max3_f32 v169, v169, v82, v83
	v_max3_f32 v169, v169, v84, v85
	v_max3_f32 v169, v169, v86, v87
	v_max3_f32 v169, v169, v88, v89
	v_max3_f32 v169, v169, v90, v91
	v_max3_f32 v169, v169, v92, v93
	v_max3_f32 v169, v169, v94, v95
	v_max3_f32 v169, v169, v64, v65
	v_max3_f32 v169, v169, v66, v67
	v_max3_f32 v169, v169, v68, v69
	v_max3_f32 v169, v169, v70, v71
	v_max3_f32 v169, v169, v72, v73
	v_max3_f32 v169, v169, v74, v75
	v_max3_f32 v169, v169, v76, v77
	v_max3_f32 v169, v169, v78, v79
	v_mov_b32_e32 v170, v169
	s_nop 1
	v_permlane32_swap_b32_e32 v169, v170
	v_max_f32_e32 v170, v170, v170
	v_max_f32_e32 v169, v169, v169
	v_max_f32_e32 v169, v169, v170
	v_sub_f32_e32 v170, v169, v160
	v_cmp_ge_f32_e32 vcc, s29, v170
	s_cmp_eq_u64 vcc, exec
	s_cbranch_scc1 .LBB0_711
	v_max_f32_e32 v169, v169, v169
	v_max_f32_e32 v170, v160, v160
	v_max_f32_e32 v169, v170, v169
	v_sub_f32_e32 v160, v160, v169
	v_exp_f32_e32 v160, v160
	s_nop 0
	v_pk_mul_f32 v[62:63], v[62:63], v[160:161] op_sel_hi:[1,0]
	v_pk_mul_f32 v[60:61], v[60:61], v[160:161] op_sel_hi:[1,0]
	v_pk_mul_f32 v[58:59], v[58:59], v[160:161] op_sel_hi:[1,0]
	v_pk_mul_f32 v[56:57], v[56:57], v[160:161] op_sel_hi:[1,0]
	v_pk_mul_f32 v[54:55], v[54:55], v[160:161] op_sel_hi:[1,0]
	v_pk_mul_f32 v[52:53], v[52:53], v[160:161] op_sel_hi:[1,0]
	v_pk_mul_f32 v[50:51], v[50:51], v[160:161] op_sel_hi:[1,0]
	v_pk_mul_f32 v[48:49], v[48:49], v[160:161] op_sel_hi:[1,0]
	v_pk_mul_f32 v[46:47], v[46:47], v[160:161] op_sel_hi:[1,0]
	v_pk_mul_f32 v[44:45], v[44:45], v[160:161] op_sel_hi:[1,0]
	v_pk_mul_f32 v[42:43], v[42:43], v[160:161] op_sel_hi:[1,0]
	v_pk_mul_f32 v[40:41], v[40:41], v[160:161] op_sel_hi:[1,0]
	v_pk_mul_f32 v[38:39], v[38:39], v[160:161] op_sel_hi:[1,0]
	v_pk_mul_f32 v[36:37], v[36:37], v[160:161] op_sel_hi:[1,0]
	v_pk_mul_f32 v[34:35], v[34:35], v[160:161] op_sel_hi:[1,0]
	v_pk_mul_f32 v[32:33], v[32:33], v[160:161] op_sel_hi:[1,0]
	v_pk_mul_f32 v[30:31], v[30:31], v[160:161] op_sel_hi:[1,0]
	v_pk_mul_f32 v[28:29], v[28:29], v[160:161] op_sel_hi:[1,0]
	v_pk_mul_f32 v[26:27], v[26:27], v[160:161] op_sel_hi:[1,0]
	v_pk_mul_f32 v[24:25], v[24:25], v[160:161] op_sel_hi:[1,0]
	v_pk_mul_f32 v[22:23], v[22:23], v[160:161] op_sel_hi:[1,0]
	v_pk_mul_f32 v[20:21], v[20:21], v[160:161] op_sel_hi:[1,0]
	v_pk_mul_f32 v[18:19], v[18:19], v[160:161] op_sel_hi:[1,0]
	v_pk_mul_f32 v[16:17], v[16:17], v[160:161] op_sel_hi:[1,0]
	v_pk_mul_f32 v[14:15], v[14:15], v[160:161] op_sel_hi:[1,0]
	v_pk_mul_f32 v[12:13], v[12:13], v[160:161] op_sel_hi:[1,0]
	v_pk_mul_f32 v[10:11], v[10:11], v[160:161] op_sel_hi:[1,0]
	v_pk_mul_f32 v[8:9], v[8:9], v[160:161] op_sel_hi:[1,0]
	v_pk_mul_f32 v[6:7], v[6:7], v[160:161] op_sel_hi:[1,0]
	v_pk_mul_f32 v[4:5], v[4:5], v[160:161] op_sel_hi:[1,0]
	v_pk_mul_f32 v[2:3], v[2:3], v[160:161] op_sel_hi:[1,0]
	v_pk_mul_f32 v[0:1], v[0:1], v[160:161] op_sel_hi:[1,0]
	v_mul_f32_e32 v147, v147, v160
	v_mov_b32_e32 v160, v169
	s_branch .LBB0_711

	.amdhsa_kernel fwd_megakernel
		.amdhsa_group_segment_fixed_size 0
		.amdhsa_private_segment_fixed_size 0
		.amdhsa_kernarg_size 560
		.amdhsa_user_sgpr_count 2
		.amdhsa_user_sgpr_dispatch_ptr 0
		.amdhsa_user_sgpr_queue_ptr 0
		.amdhsa_user_sgpr_kernarg_segment_ptr 1
		.amdhsa_user_sgpr_dispatch_id 0
		.amdhsa_user_sgpr_kernarg_preload_length 0
		.amdhsa_user_sgpr_kernarg_preload_offset 0
		.amdhsa_user_sgpr_private_segment_size 0
		.amdhsa_uses_dynamic_stack 0
		.amdhsa_enable_private_segment 0
		.amdhsa_system_sgpr_workgroup_id_x 1
		.amdhsa_system_sgpr_workgroup_id_y 0
		.amdhsa_system_sgpr_workgroup_id_z 0
		.amdhsa_system_sgpr_workgroup_info 0
		.amdhsa_system_vgpr_workitem_id 2
		.amdhsa_next_free_vgpr 248
		.amdhsa_next_free_sgpr 102
		.amdhsa_accum_offset 248
		.amdhsa_reserve_vcc 1
		.amdhsa_float_round_mode_32 0
		.amdhsa_float_round_mode_16_64 0
		.amdhsa_float_denorm_mode_32 3
		.amdhsa_float_denorm_mode_16_64 3
		.amdhsa_dx10_clamp 1
		.amdhsa_ieee_mode 1
		.amdhsa_fp16_overflow 0
		.amdhsa_tg_split 0
		.amdhsa_exception_fp_ieee_invalid_op 0
		.amdhsa_exception_fp_denorm_src 0
		.amdhsa_exception_fp_ieee_div_zero 0
		.amdhsa_exception_fp_ieee_overflow 0
		.amdhsa_exception_fp_ieee_underflow 0
		.amdhsa_exception_fp_ieee_inexact 0
		.amdhsa_exception_int_div_zero 0
	.end_amdhsa_kernel

amdhsa.kernels:
  - .agpr_count:     0
    .args:
      - .offset:         0
        .size:           304
        .value_kind:     by_value
      - .offset:         304
        .size:           4
        .value_kind:     hidden_block_count_x
      - .offset:         308
        .size:           4
        .value_kind:     hidden_block_count_y
      - .offset:         312
        .size:           4
        .value_kind:     hidden_block_count_z
      - .offset:         316
        .size:           2
        .value_kind:     hidden_group_size_x
      - .offset:         318
        .size:           2
        .value_kind:     hidden_group_size_y
      - .offset:         320
        .size:           2
        .value_kind:     hidden_group_size_z
      - .offset:         322
        .size:           2
        .value_kind:     hidden_remainder_x
      - .offset:         324
        .size:           2
        .value_kind:     hidden_remainder_y
      - .offset:         326
        .size:           2
        .value_kind:     hidden_remainder_z
      - .offset:         344
        .size:           8
        .value_kind:     hidden_global_offset_x
      - .offset:         352
        .size:           8
        .value_kind:     hidden_global_offset_y
      - .offset:         360
        .size:           8
        .value_kind:     hidden_global_offset_z
      - .offset:         368
        .size:           2
        .value_kind:     hidden_grid_dims
      - .offset:         392
        .size:           8
        .value_kind:     hidden_multigrid_sync_arg
      - .offset:         424
        .size:           4
        .value_kind:     hidden_dynamic_lds_size
    .group_segment_fixed_size: 0
    .kernarg_segment_align: 8
    .kernarg_segment_size: 560
    .language:       OpenCL C
    .language_version:
      - 2
      - 0
    .max_flat_workgroup_size: 512
    .name:           fwd_megakernel
    .private_segment_fixed_size: 0
    .sgpr_count:     108
    .sgpr_spill_count: 214
    .symbol:         fwd_megakernel.kd
    .uniform_work_group_size: 1
    .uses_dynamic_stack: false
    .vgpr_count:     248
    .vgpr_spill_count: 0
    .wavefront_size: 64
